# non-temporal (nt) hint on the read-once residual loads in the out-proj and mlp-out epilogues, on top of v91
# speedup vs baseline: 1.0087x; 1.0087x over previous
.LBB0_803:
	v_lshl_add_u32 v140, s91, 8, v3
	v_lshl_or_b32 v138, s90, 8, v143
	v_ashrrev_i32_e32 v141, 31, v140
	v_ashrrev_i32_e32 v139, 31, v138
	v_lshlrev_b64 v[146:147], 10, v[140:141]
	v_lshl_add_u64 v[154:155], v[146:147], 0, v[138:139]
	v_lshlrev_b64 v[156:157], 2, v[154:155]
	v_lshl_add_u64 v[158:159], s[28:29], 0, v[156:157]
	global_load_dwordx4 v[146:149], v[158:159], off nt
	global_load_dwordx4 v[150:153], v[158:159], off offset:16 nt
	v_lshl_add_u64 v[160:161], v[154:155], 1, s[50:51]
	v_lshl_add_u64 v[162:163], s[44:45], 0, v[156:157]
	v_xor_b32_e32 v145, 32, v204
	s_waitcnt vmcnt(0)
	v_pk_add_f32 v[130:131], v[130:131], v[148:149]
	v_pk_add_f32 v[128:129], v[128:129], v[146:147]
	v_pk_add_f32 v[148:149], v[126:127], v[152:153]
	v_pk_add_f32 v[146:147], v[124:125], v[150:151]
	global_store_dwordx4 v[162:163], v[128:131], off
	global_store_dwordx4 v[162:163], v[146:149], off offset:16
	v_cvt_pk_bf16_f32 v124, v128, v129
	v_cvt_pk_bf16_f32 v125, v130, v131
	v_cvt_pk_bf16_f32 v126, v146, v147
	v_cvt_pk_bf16_f32 v127, v148, v149
	global_store_dwordx4 v[160:161], v[124:127], off
	global_load_dwordx4 v[150:153], v[158:159], off offset:512 nt
	global_load_dwordx4 v[154:157], v[158:159], off offset:528 nt
	v_mul_f32_e32 v126, v129, v129
	v_mul_f32_e32 v127, v131, v131
	v_mul_f32_e32 v129, v147, v147
	v_mul_f32_e32 v131, v149, v149
	v_fmac_f32_e32 v126, v128, v128
	v_fmac_f32_e32 v127, v130, v130
	v_fmac_f32_e32 v129, v146, v146
	v_fmac_f32_e32 v131, v148, v148
	v_add_f32_e32 v126, v126, v127
	v_add_f32_e32 v127, v129, v131
	v_add_f32_e32 v130, v126, v127
	v_and_b32_e32 v125, 64, v204
	v_xor_b32_e32 v124, 16, v204
	v_add_u32_e32 v125, 64, v125
	v_cmp_lt_i32_e32 vcc, v124, v125
	s_waitcnt vmcnt(1)
	v_pk_add_f32 v[122:123], v[122:123], v[152:153]
	v_pk_add_f32 v[120:121], v[120:121], v[150:151]
	s_waitcnt vmcnt(0)
	v_pk_add_f32 v[128:129], v[118:119], v[156:157]
	v_pk_add_f32 v[126:127], v[116:117], v[154:155]
	v_mul_f32_e32 v116, v121, v121
	v_mul_f32_e32 v117, v123, v123
	v_mul_f32_e32 v118, v127, v127
	v_mul_f32_e32 v119, v129, v129
	v_fmac_f32_e32 v116, v120, v120
	v_fmac_f32_e32 v117, v122, v122
	v_fmac_f32_e32 v118, v126, v126
	v_fmac_f32_e32 v119, v128, v128
	v_add_f32_e32 v116, v116, v117
	v_add_f32_e32 v117, v118, v119
	v_cndmask_b32_e32 v124, v204, v124, vcc
	v_add_f32_e32 v116, v116, v117
	v_lshlrev_b32_e32 v124, 2, v124
	v_add_f32_e32 v116, v130, v116
	ds_bpermute_b32 v117, v124, v116
	v_cmp_lt_i32_e32 vcc, v145, v125
	global_store_dwordx4 v[162:163], v[120:123], off offset:512
	global_store_dwordx4 v[162:163], v[126:129], off offset:528
	v_cndmask_b32_e32 v118, v204, v145, vcc
	v_lshlrev_b32_e32 v118, 2, v118
	s_waitcnt lgkmcnt(0)
	v_add_f32_e32 v116, v116, v117
	ds_bpermute_b32 v117, v118, v116
	v_cvt_pk_bf16_f32 v120, v120, v121
	v_cvt_pk_bf16_f32 v121, v122, v123
	v_cvt_pk_bf16_f32 v122, v126, v127
	v_cvt_pk_bf16_f32 v123, v128, v129
	global_store_dwordx4 v[160:161], v[120:123], off offset:256
	s_and_saveexec_b64 s[24:25], s[40:41]
	s_cbranch_execz .LBB0_805
	v_lshl_add_u64 v[120:121], v[140:141], 2, s[46:47]
	s_waitcnt lgkmcnt(0)
	v_add_f32_e32 v116, v116, v117
	global_atomic_add_f32 v[120:121], v116, off
.LBB0_805:
	s_or_b64 exec, exec, s[24:25]
	v_or_b32_e32 v116, 16, v140
	s_waitcnt lgkmcnt(0)
	v_ashrrev_i32_e32 v117, 31, v116
	v_lshlrev_b64 v[120:121], 10, v[116:117]
	v_lshl_add_u64 v[130:131], v[120:121], 0, v[138:139]
	v_lshlrev_b64 v[146:147], 2, v[130:131]
	v_lshl_add_u64 v[148:149], s[28:29], 0, v[146:147]
	global_load_dwordx4 v[120:123], v[148:149], off nt
	global_load_dwordx4 v[126:129], v[148:149], off offset:16 nt
	v_lshl_add_u64 v[130:131], v[130:131], 1, s[50:51]
	v_lshl_add_u64 v[146:147], s[44:45], 0, v[146:147]
	s_waitcnt vmcnt(1)
	v_pk_add_f32 v[114:115], v[114:115], v[122:123]
	v_pk_add_f32 v[112:113], v[112:113], v[120:121]
	s_waitcnt vmcnt(0)
	v_pk_add_f32 v[110:111], v[110:111], v[128:129]
	v_pk_add_f32 v[108:109], v[108:109], v[126:127]
	global_store_dwordx4 v[146:147], v[112:115], off
	global_store_dwordx4 v[146:147], v[108:111], off offset:16
	v_cvt_pk_bf16_f32 v120, v112, v113
	v_cvt_pk_bf16_f32 v121, v114, v115
	v_cvt_pk_bf16_f32 v122, v108, v109
	v_cvt_pk_bf16_f32 v123, v110, v111
	global_store_dwordx4 v[130:131], v[120:123], off
	global_load_dwordx4 v[120:123], v[148:149], off offset:512 nt
	s_nop 0
	global_load_dwordx4 v[126:129], v[148:149], off offset:528 nt
	v_mul_f32_e32 v113, v113, v113
	v_mul_f32_e32 v115, v115, v115
	v_mul_f32_e32 v109, v109, v109
	v_mul_f32_e32 v111, v111, v111
	v_fmac_f32_e32 v113, v112, v112
	v_fmac_f32_e32 v115, v114, v114
	v_fmac_f32_e32 v109, v108, v108
	v_fmac_f32_e32 v111, v110, v110
	v_add_f32_e32 v108, v113, v115
	v_add_f32_e32 v109, v109, v111
	v_add_f32_e32 v112, v108, v109
	s_waitcnt vmcnt(1)
	v_pk_add_f32 v[106:107], v[106:107], v[122:123]
	v_pk_add_f32 v[104:105], v[104:105], v[120:121]
	s_waitcnt vmcnt(0)
	v_pk_add_f32 v[110:111], v[102:103], v[128:129]
	v_pk_add_f32 v[108:109], v[100:101], v[126:127]
	v_mul_f32_e32 v100, v105, v105
	v_mul_f32_e32 v101, v107, v107
	v_mul_f32_e32 v102, v109, v109
	v_mul_f32_e32 v103, v111, v111
	v_fmac_f32_e32 v100, v104, v104
	v_fmac_f32_e32 v101, v106, v106
	v_fmac_f32_e32 v102, v108, v108
	v_fmac_f32_e32 v103, v110, v110
	v_add_f32_e32 v100, v100, v101
	v_add_f32_e32 v101, v102, v103
	v_add_f32_e32 v100, v100, v101
	v_add_f32_e32 v100, v112, v100
	ds_bpermute_b32 v101, v124, v100
	global_store_dwordx4 v[146:147], v[104:107], off offset:512
	global_store_dwordx4 v[146:147], v[108:111], off offset:528
	v_cvt_pk_bf16_f32 v102, v104, v105
	v_cvt_pk_bf16_f32 v103, v106, v107
	s_waitcnt lgkmcnt(0)
	v_add_f32_e32 v100, v100, v101
	ds_bpermute_b32 v101, v118, v100
	v_cvt_pk_bf16_f32 v104, v108, v109
	v_cvt_pk_bf16_f32 v105, v110, v111
	global_store_dwordx4 v[130:131], v[102:105], off offset:256
	s_and_saveexec_b64 s[24:25], s[40:41]
	s_cbranch_execz .LBB0_807
	v_lshl_add_u64 v[102:103], v[116:117], 2, s[46:47]
	s_waitcnt lgkmcnt(0)
	v_add_f32_e32 v100, v100, v101
	global_atomic_add_f32 v[102:103], v100, off
.LBB0_807:
	s_or_b64 exec, exec, s[24:25]
	v_or_b32_e32 v100, 32, v140
	s_waitcnt lgkmcnt(0)
	v_ashrrev_i32_e32 v101, 31, v100
	v_lshlrev_b64 v[102:103], 10, v[100:101]
	v_lshl_add_u64 v[110:111], v[102:103], 0, v[138:139]
	v_lshlrev_b64 v[112:113], 2, v[110:111]
	v_lshl_add_u64 v[114:115], s[28:29], 0, v[112:113]
	global_load_dwordx4 v[102:105], v[114:115], off nt
	global_load_dwordx4 v[106:109], v[114:115], off offset:16 nt
	v_lshl_add_u64 v[110:111], v[110:111], 1, s[50:51]
	v_lshl_add_u64 v[112:113], s[44:45], 0, v[112:113]
	s_waitcnt vmcnt(1)
	v_pk_add_f32 v[98:99], v[98:99], v[104:105]
	v_pk_add_f32 v[96:97], v[96:97], v[102:103]
	s_waitcnt vmcnt(0)
	v_pk_add_f32 v[94:95], v[94:95], v[108:109]
	v_pk_add_f32 v[92:93], v[92:93], v[106:107]
	global_store_dwordx4 v[112:113], v[96:99], off
	global_store_dwordx4 v[112:113], v[92:95], off offset:16
	v_cvt_pk_bf16_f32 v102, v96, v97
	v_cvt_pk_bf16_f32 v103, v98, v99
	v_cvt_pk_bf16_f32 v104, v92, v93
	v_cvt_pk_bf16_f32 v105, v94, v95
	global_store_dwordx4 v[110:111], v[102:105], off
	global_load_dwordx4 v[102:105], v[114:115], off offset:512 nt
	s_nop 0
	global_load_dwordx4 v[106:109], v[114:115], off offset:528 nt
	v_mul_f32_e32 v97, v97, v97
	v_mul_f32_e32 v99, v99, v99
	v_mul_f32_e32 v93, v93, v93
	v_mul_f32_e32 v95, v95, v95
	v_fmac_f32_e32 v97, v96, v96
	v_fmac_f32_e32 v99, v98, v98
	v_fmac_f32_e32 v93, v92, v92
	v_fmac_f32_e32 v95, v94, v94
	v_add_f32_e32 v92, v97, v99
	v_add_f32_e32 v93, v93, v95
	v_add_f32_e32 v96, v92, v93
	s_waitcnt vmcnt(1)
	v_pk_add_f32 v[90:91], v[90:91], v[104:105]
	v_pk_add_f32 v[88:89], v[88:89], v[102:103]
	s_waitcnt vmcnt(0)
	v_pk_add_f32 v[94:95], v[86:87], v[108:109]
	v_pk_add_f32 v[92:93], v[84:85], v[106:107]
	v_mul_f32_e32 v84, v89, v89
	v_mul_f32_e32 v85, v91, v91
	v_mul_f32_e32 v86, v93, v93
	v_mul_f32_e32 v87, v95, v95
	v_fmac_f32_e32 v84, v88, v88
	v_fmac_f32_e32 v85, v90, v90
	v_fmac_f32_e32 v86, v92, v92
	v_fmac_f32_e32 v87, v94, v94
	v_add_f32_e32 v84, v84, v85
	v_add_f32_e32 v85, v86, v87
	v_add_f32_e32 v84, v84, v85
	v_add_f32_e32 v84, v96, v84
	ds_bpermute_b32 v85, v124, v84
	global_store_dwordx4 v[112:113], v[88:91], off offset:512
	global_store_dwordx4 v[112:113], v[92:95], off offset:528
	v_cvt_pk_bf16_f32 v86, v88, v89
	v_cvt_pk_bf16_f32 v87, v90, v91
	s_waitcnt lgkmcnt(0)
	v_add_f32_e32 v84, v84, v85
	ds_bpermute_b32 v85, v118, v84
	v_cvt_pk_bf16_f32 v88, v92, v93
	v_cvt_pk_bf16_f32 v89, v94, v95
	global_store_dwordx4 v[110:111], v[86:89], off offset:256
	s_and_saveexec_b64 s[24:25], s[40:41]
	s_cbranch_execz .LBB0_809
	v_lshl_add_u64 v[86:87], v[100:101], 2, s[46:47]
	s_waitcnt lgkmcnt(0)
	v_add_f32_e32 v84, v84, v85
	global_atomic_add_f32 v[86:87], v84, off
.LBB0_809:
	s_or_b64 exec, exec, s[24:25]
	v_or_b32_e32 v84, 48, v140
	s_waitcnt lgkmcnt(0)
	v_ashrrev_i32_e32 v85, 31, v84
	v_lshlrev_b64 v[86:87], 10, v[84:85]
	v_lshl_add_u64 v[94:95], v[86:87], 0, v[138:139]
	v_lshlrev_b64 v[96:97], 2, v[94:95]
	v_lshl_add_u64 v[98:99], s[28:29], 0, v[96:97]
	global_load_dwordx4 v[86:89], v[98:99], off nt
	global_load_dwordx4 v[90:93], v[98:99], off offset:16 nt
	v_lshl_add_u64 v[94:95], v[94:95], 1, s[50:51]
	v_lshl_add_u64 v[96:97], s[44:45], 0, v[96:97]
	s_waitcnt vmcnt(1)
	v_pk_add_f32 v[82:83], v[82:83], v[88:89]
	v_pk_add_f32 v[80:81], v[80:81], v[86:87]
	s_waitcnt vmcnt(0)
	v_pk_add_f32 v[78:79], v[78:79], v[92:93]
	v_pk_add_f32 v[76:77], v[76:77], v[90:91]
	global_store_dwordx4 v[96:97], v[80:83], off
	global_store_dwordx4 v[96:97], v[76:79], off offset:16
	v_cvt_pk_bf16_f32 v86, v80, v81
	v_cvt_pk_bf16_f32 v87, v82, v83
	v_cvt_pk_bf16_f32 v88, v76, v77
	v_cvt_pk_bf16_f32 v89, v78, v79
	global_store_dwordx4 v[94:95], v[86:89], off
	global_load_dwordx4 v[86:89], v[98:99], off offset:512 nt
	s_nop 0
	global_load_dwordx4 v[90:93], v[98:99], off offset:528 nt
	v_mul_f32_e32 v81, v81, v81
	v_mul_f32_e32 v83, v83, v83
	v_mul_f32_e32 v77, v77, v77
	v_mul_f32_e32 v79, v79, v79
	v_fmac_f32_e32 v81, v80, v80
	v_fmac_f32_e32 v83, v82, v82
	v_fmac_f32_e32 v77, v76, v76
	v_fmac_f32_e32 v79, v78, v78
	v_add_f32_e32 v76, v81, v83
	v_add_f32_e32 v77, v77, v79
	v_add_f32_e32 v80, v76, v77
	s_waitcnt vmcnt(1)
	v_pk_add_f32 v[74:75], v[74:75], v[88:89]
	v_pk_add_f32 v[72:73], v[72:73], v[86:87]
	s_waitcnt vmcnt(0)
	v_pk_add_f32 v[78:79], v[70:71], v[92:93]
	v_pk_add_f32 v[76:77], v[68:69], v[90:91]
	v_mul_f32_e32 v68, v73, v73
	v_mul_f32_e32 v69, v75, v75
	v_mul_f32_e32 v70, v77, v77
	v_mul_f32_e32 v71, v79, v79
	v_fmac_f32_e32 v68, v72, v72
	v_fmac_f32_e32 v69, v74, v74
	v_fmac_f32_e32 v70, v76, v76
	v_fmac_f32_e32 v71, v78, v78
	v_add_f32_e32 v68, v68, v69
	v_add_f32_e32 v69, v70, v71
	v_add_f32_e32 v68, v68, v69
	v_add_f32_e32 v68, v80, v68
	ds_bpermute_b32 v69, v124, v68
	global_store_dwordx4 v[96:97], v[72:75], off offset:512
	global_store_dwordx4 v[96:97], v[76:79], off offset:528
	v_cvt_pk_bf16_f32 v70, v72, v73
	v_cvt_pk_bf16_f32 v71, v74, v75
	s_waitcnt lgkmcnt(0)
	v_add_f32_e32 v68, v68, v69
	ds_bpermute_b32 v69, v118, v68
	v_cvt_pk_bf16_f32 v72, v76, v77
	v_cvt_pk_bf16_f32 v73, v78, v79
	global_store_dwordx4 v[94:95], v[70:73], off offset:256
	s_and_saveexec_b64 s[24:25], s[40:41]
	s_cbranch_execz .LBB0_811
	v_lshl_add_u64 v[70:71], v[84:85], 2, s[46:47]
	s_waitcnt lgkmcnt(0)
	v_add_f32_e32 v68, v68, v69
	global_atomic_add_f32 v[70:71], v68, off
.LBB0_811:
	s_or_b64 exec, exec, s[24:25]
	v_add_u32_e32 v68, 0x80, v140
	s_waitcnt lgkmcnt(0)
	v_ashrrev_i32_e32 v69, 31, v68
	v_lshlrev_b64 v[70:71], 10, v[68:69]
	v_lshl_add_u64 v[78:79], v[70:71], 0, v[138:139]
	v_lshlrev_b64 v[80:81], 2, v[78:79]
	v_lshl_add_u64 v[82:83], s[28:29], 0, v[80:81]
	global_load_dwordx4 v[70:73], v[82:83], off nt
	global_load_dwordx4 v[74:77], v[82:83], off offset:16 nt
	v_lshl_add_u64 v[78:79], v[78:79], 1, s[50:51]
	v_lshl_add_u64 v[80:81], s[44:45], 0, v[80:81]
	s_waitcnt vmcnt(1)
	v_pk_add_f32 v[66:67], v[66:67], v[72:73]
	v_pk_add_f32 v[64:65], v[64:65], v[70:71]
	s_waitcnt vmcnt(0)
	v_pk_add_f32 v[62:63], v[62:63], v[76:77]
	v_pk_add_f32 v[60:61], v[60:61], v[74:75]
	global_store_dwordx4 v[80:81], v[64:67], off
	global_store_dwordx4 v[80:81], v[60:63], off offset:16
	v_cvt_pk_bf16_f32 v70, v64, v65
	v_cvt_pk_bf16_f32 v71, v66, v67
	v_cvt_pk_bf16_f32 v72, v60, v61
	v_cvt_pk_bf16_f32 v73, v62, v63
	global_store_dwordx4 v[78:79], v[70:73], off
	global_load_dwordx4 v[70:73], v[82:83], off offset:512 nt
	s_nop 0
	global_load_dwordx4 v[74:77], v[82:83], off offset:528 nt
	v_mul_f32_e32 v65, v65, v65
	v_mul_f32_e32 v67, v67, v67
	v_mul_f32_e32 v61, v61, v61
	v_mul_f32_e32 v63, v63, v63
	v_fmac_f32_e32 v65, v64, v64
	v_fmac_f32_e32 v67, v66, v66
	v_fmac_f32_e32 v61, v60, v60
	v_fmac_f32_e32 v63, v62, v62
	v_add_f32_e32 v60, v65, v67
	v_add_f32_e32 v61, v61, v63
	v_add_f32_e32 v64, v60, v61
	s_waitcnt vmcnt(1)
	v_pk_add_f32 v[58:59], v[58:59], v[72:73]
	v_pk_add_f32 v[56:57], v[56:57], v[70:71]
	s_waitcnt vmcnt(0)
	v_pk_add_f32 v[62:63], v[54:55], v[76:77]
	v_pk_add_f32 v[60:61], v[52:53], v[74:75]
	v_mul_f32_e32 v52, v57, v57
	v_mul_f32_e32 v53, v59, v59
	v_mul_f32_e32 v54, v61, v61
	v_mul_f32_e32 v55, v63, v63
	v_fmac_f32_e32 v52, v56, v56
	v_fmac_f32_e32 v53, v58, v58
	v_fmac_f32_e32 v54, v60, v60
	v_fmac_f32_e32 v55, v62, v62
	v_add_f32_e32 v52, v52, v53
	v_add_f32_e32 v53, v54, v55
	v_add_f32_e32 v52, v52, v53
	v_add_f32_e32 v52, v64, v52
	ds_bpermute_b32 v53, v124, v52
	global_store_dwordx4 v[80:81], v[56:59], off offset:512
	global_store_dwordx4 v[80:81], v[60:63], off offset:528
	v_cvt_pk_bf16_f32 v54, v56, v57
	v_cvt_pk_bf16_f32 v55, v58, v59
	s_waitcnt lgkmcnt(0)
	v_add_f32_e32 v52, v52, v53
	ds_bpermute_b32 v53, v118, v52
	v_cvt_pk_bf16_f32 v56, v60, v61
	v_cvt_pk_bf16_f32 v57, v62, v63
	global_store_dwordx4 v[78:79], v[54:57], off offset:256
	s_and_saveexec_b64 s[24:25], s[40:41]
	s_cbranch_execz .LBB0_813
	v_lshl_add_u64 v[54:55], v[68:69], 2, s[46:47]
	s_waitcnt lgkmcnt(0)
	v_add_f32_e32 v52, v52, v53
	global_atomic_add_f32 v[54:55], v52, off
.LBB0_813:
	s_or_b64 exec, exec, s[24:25]
	v_add_u32_e32 v52, 0x90, v140
	s_waitcnt lgkmcnt(0)
	v_ashrrev_i32_e32 v53, 31, v52
	v_lshlrev_b64 v[54:55], 10, v[52:53]
	v_lshl_add_u64 v[62:63], v[54:55], 0, v[138:139]
	v_lshlrev_b64 v[64:65], 2, v[62:63]
	v_lshl_add_u64 v[66:67], s[28:29], 0, v[64:65]
	global_load_dwordx4 v[54:57], v[66:67], off nt
	global_load_dwordx4 v[58:61], v[66:67], off offset:16 nt
	v_lshl_add_u64 v[62:63], v[62:63], 1, s[50:51]
	v_lshl_add_u64 v[64:65], s[44:45], 0, v[64:65]
	s_waitcnt vmcnt(1)
	v_pk_add_f32 v[50:51], v[50:51], v[56:57]
	v_pk_add_f32 v[48:49], v[48:49], v[54:55]
	s_waitcnt vmcnt(0)
	v_pk_add_f32 v[46:47], v[46:47], v[60:61]
	v_pk_add_f32 v[44:45], v[44:45], v[58:59]
	global_store_dwordx4 v[64:65], v[48:51], off
	global_store_dwordx4 v[64:65], v[44:47], off offset:16
	v_cvt_pk_bf16_f32 v54, v48, v49
	v_cvt_pk_bf16_f32 v55, v50, v51
	v_cvt_pk_bf16_f32 v56, v44, v45
	v_cvt_pk_bf16_f32 v57, v46, v47
	global_store_dwordx4 v[62:63], v[54:57], off
	global_load_dwordx4 v[54:57], v[66:67], off offset:512 nt
	s_nop 0
	global_load_dwordx4 v[58:61], v[66:67], off offset:528 nt
	v_mul_f32_e32 v49, v49, v49
	v_mul_f32_e32 v51, v51, v51
	v_mul_f32_e32 v45, v45, v45
	v_mul_f32_e32 v47, v47, v47
	v_fmac_f32_e32 v49, v48, v48
	v_fmac_f32_e32 v51, v50, v50
	v_fmac_f32_e32 v45, v44, v44
	v_fmac_f32_e32 v47, v46, v46
	v_add_f32_e32 v44, v49, v51
	v_add_f32_e32 v45, v45, v47
	v_add_f32_e32 v48, v44, v45
	s_waitcnt vmcnt(1)
	v_pk_add_f32 v[42:43], v[42:43], v[56:57]
	v_pk_add_f32 v[40:41], v[40:41], v[54:55]
	s_waitcnt vmcnt(0)
	v_pk_add_f32 v[46:47], v[38:39], v[60:61]
	v_pk_add_f32 v[44:45], v[36:37], v[58:59]
	v_mul_f32_e32 v36, v41, v41
	v_mul_f32_e32 v37, v43, v43
	v_mul_f32_e32 v38, v45, v45
	v_mul_f32_e32 v39, v47, v47
	v_fmac_f32_e32 v36, v40, v40
	v_fmac_f32_e32 v37, v42, v42
	v_fmac_f32_e32 v38, v44, v44
	v_fmac_f32_e32 v39, v46, v46
	v_add_f32_e32 v36, v36, v37
	v_add_f32_e32 v37, v38, v39
	v_add_f32_e32 v36, v36, v37
	v_add_f32_e32 v36, v48, v36
	ds_bpermute_b32 v37, v124, v36
	global_store_dwordx4 v[64:65], v[40:43], off offset:512
	global_store_dwordx4 v[64:65], v[44:47], off offset:528
	v_cvt_pk_bf16_f32 v38, v40, v41
	v_cvt_pk_bf16_f32 v39, v42, v43
	s_waitcnt lgkmcnt(0)
	v_add_f32_e32 v36, v36, v37
	ds_bpermute_b32 v37, v118, v36
	v_cvt_pk_bf16_f32 v40, v44, v45
	v_cvt_pk_bf16_f32 v41, v46, v47
	global_store_dwordx4 v[62:63], v[38:41], off offset:256
	s_and_saveexec_b64 s[24:25], s[40:41]
	s_cbranch_execz .LBB0_815
	v_lshl_add_u64 v[38:39], v[52:53], 2, s[46:47]
	s_waitcnt lgkmcnt(0)
	v_add_f32_e32 v36, v36, v37
	global_atomic_add_f32 v[38:39], v36, off
.LBB0_815:
	s_or_b64 exec, exec, s[24:25]
	v_add_u32_e32 v36, 0xa0, v140
	s_waitcnt lgkmcnt(0)
	v_ashrrev_i32_e32 v37, 31, v36
	v_lshlrev_b64 v[38:39], 10, v[36:37]
	v_lshl_add_u64 v[46:47], v[38:39], 0, v[138:139]
	v_lshlrev_b64 v[48:49], 2, v[46:47]
	v_lshl_add_u64 v[50:51], s[28:29], 0, v[48:49]
	global_load_dwordx4 v[38:41], v[50:51], off nt
	global_load_dwordx4 v[42:45], v[50:51], off offset:16 nt
	v_lshl_add_u64 v[46:47], v[46:47], 1, s[50:51]
	v_lshl_add_u64 v[48:49], s[44:45], 0, v[48:49]
	s_waitcnt vmcnt(1)
	v_pk_add_f32 v[34:35], v[34:35], v[40:41]
	v_pk_add_f32 v[32:33], v[32:33], v[38:39]
	s_waitcnt vmcnt(0)
	v_pk_add_f32 v[30:31], v[30:31], v[44:45]
	v_pk_add_f32 v[28:29], v[28:29], v[42:43]
	global_store_dwordx4 v[48:49], v[32:35], off
	global_store_dwordx4 v[48:49], v[28:31], off offset:16
	v_cvt_pk_bf16_f32 v38, v32, v33
	v_cvt_pk_bf16_f32 v39, v34, v35
	v_cvt_pk_bf16_f32 v40, v28, v29
	v_cvt_pk_bf16_f32 v41, v30, v31
	global_store_dwordx4 v[46:47], v[38:41], off
	global_load_dwordx4 v[38:41], v[50:51], off offset:512 nt
	s_nop 0
	global_load_dwordx4 v[42:45], v[50:51], off offset:528 nt
	v_mul_f32_e32 v33, v33, v33
	v_mul_f32_e32 v35, v35, v35
	v_mul_f32_e32 v29, v29, v29
	v_mul_f32_e32 v31, v31, v31
	v_fmac_f32_e32 v33, v32, v32
	v_fmac_f32_e32 v35, v34, v34
	v_fmac_f32_e32 v29, v28, v28
	v_fmac_f32_e32 v31, v30, v30
	v_add_f32_e32 v28, v33, v35
	v_add_f32_e32 v29, v29, v31
	v_add_f32_e32 v32, v28, v29
	s_waitcnt vmcnt(1)
	v_pk_add_f32 v[26:27], v[26:27], v[40:41]
	v_pk_add_f32 v[24:25], v[24:25], v[38:39]
	s_waitcnt vmcnt(0)
	v_pk_add_f32 v[30:31], v[22:23], v[44:45]
	v_pk_add_f32 v[28:29], v[20:21], v[42:43]
	v_mul_f32_e32 v20, v25, v25
	v_mul_f32_e32 v21, v27, v27
	v_mul_f32_e32 v22, v29, v29
	v_mul_f32_e32 v23, v31, v31
	v_fmac_f32_e32 v20, v24, v24
	v_fmac_f32_e32 v21, v26, v26
	v_fmac_f32_e32 v22, v28, v28
	v_fmac_f32_e32 v23, v30, v30
	v_add_f32_e32 v20, v20, v21
	v_add_f32_e32 v21, v22, v23
	v_add_f32_e32 v20, v20, v21
	v_add_f32_e32 v20, v32, v20
	ds_bpermute_b32 v21, v124, v20
	global_store_dwordx4 v[48:49], v[24:27], off offset:512
	global_store_dwordx4 v[48:49], v[28:31], off offset:528
	v_cvt_pk_bf16_f32 v22, v24, v25
	v_cvt_pk_bf16_f32 v23, v26, v27
	s_waitcnt lgkmcnt(0)
	v_add_f32_e32 v20, v20, v21
	ds_bpermute_b32 v21, v118, v20
	v_cvt_pk_bf16_f32 v24, v28, v29
	v_cvt_pk_bf16_f32 v25, v30, v31
	global_store_dwordx4 v[46:47], v[22:25], off offset:256
	s_and_saveexec_b64 s[24:25], s[40:41]
	s_cbranch_execz .LBB0_817
	v_lshl_add_u64 v[22:23], v[36:37], 2, s[46:47]
	s_waitcnt lgkmcnt(0)
	v_add_f32_e32 v20, v20, v21
	global_atomic_add_f32 v[22:23], v20, off
.LBB0_817:
	s_or_b64 exec, exec, s[24:25]
	v_add_u32_e32 v20, 0xb0, v140
	s_waitcnt lgkmcnt(0)
	v_ashrrev_i32_e32 v21, 31, v20
	v_lshlrev_b64 v[22:23], 10, v[20:21]
	v_lshl_add_u64 v[30:31], v[22:23], 0, v[138:139]
	v_lshlrev_b64 v[32:33], 2, v[30:31]
	v_lshl_add_u64 v[34:35], s[28:29], 0, v[32:33]
	global_load_dwordx4 v[22:25], v[34:35], off nt
	global_load_dwordx4 v[26:29], v[34:35], off offset:16 nt
	v_lshl_add_u64 v[30:31], v[30:31], 1, s[50:51]
	v_lshl_add_u64 v[32:33], s[44:45], 0, v[32:33]
	s_waitcnt vmcnt(1)
	v_pk_add_f32 v[18:19], v[18:19], v[24:25]
	v_pk_add_f32 v[16:17], v[16:17], v[22:23]
	s_waitcnt vmcnt(0)
	v_pk_add_f32 v[14:15], v[14:15], v[28:29]
	v_pk_add_f32 v[12:13], v[12:13], v[26:27]
	global_store_dwordx4 v[32:33], v[16:19], off
	global_store_dwordx4 v[32:33], v[12:15], off offset:16
	v_cvt_pk_bf16_f32 v22, v16, v17
	v_cvt_pk_bf16_f32 v23, v18, v19
	v_cvt_pk_bf16_f32 v24, v12, v13
	v_cvt_pk_bf16_f32 v25, v14, v15
	global_store_dwordx4 v[30:31], v[22:25], off
	global_load_dwordx4 v[22:25], v[34:35], off offset:512 nt
	s_nop 0
	global_load_dwordx4 v[26:29], v[34:35], off offset:528 nt
	v_mul_f32_e32 v17, v17, v17
	v_mul_f32_e32 v19, v19, v19
	v_mul_f32_e32 v13, v13, v13
	v_mul_f32_e32 v15, v15, v15
	v_fmac_f32_e32 v17, v16, v16
	v_fmac_f32_e32 v19, v18, v18
	v_fmac_f32_e32 v13, v12, v12
	v_fmac_f32_e32 v15, v14, v14
	v_add_f32_e32 v12, v17, v19
	v_add_f32_e32 v13, v13, v15
	v_add_f32_e32 v16, v12, v13
	s_waitcnt vmcnt(1)
	v_pk_add_f32 v[10:11], v[10:11], v[24:25]
	v_pk_add_f32 v[8:9], v[8:9], v[22:23]
	s_waitcnt vmcnt(0)
	v_pk_add_f32 v[14:15], v[6:7], v[28:29]
	v_pk_add_f32 v[12:13], v[4:5], v[26:27]
	v_mul_f32_e32 v4, v9, v9
	v_mul_f32_e32 v5, v11, v11
	v_mul_f32_e32 v6, v13, v13
	v_mul_f32_e32 v7, v15, v15
	v_fmac_f32_e32 v4, v8, v8
	v_fmac_f32_e32 v5, v10, v10
	v_fmac_f32_e32 v6, v12, v12
	v_fmac_f32_e32 v7, v14, v14
	v_add_f32_e32 v4, v4, v5
	v_add_f32_e32 v5, v6, v7
	v_add_f32_e32 v4, v4, v5
	v_add_f32_e32 v4, v16, v4
	ds_bpermute_b32 v5, v124, v4
	global_store_dwordx4 v[32:33], v[8:11], off offset:512
	global_store_dwordx4 v[32:33], v[12:15], off offset:528
	v_cvt_pk_bf16_f32 v6, v8, v9
	v_cvt_pk_bf16_f32 v7, v10, v11
	s_waitcnt lgkmcnt(0)
	v_add_f32_e32 v4, v4, v5
	ds_bpermute_b32 v5, v118, v4
	v_cvt_pk_bf16_f32 v8, v12, v13
	v_cvt_pk_bf16_f32 v9, v14, v15
	global_store_dwordx4 v[30:31], v[6:9], off offset:256
	s_and_saveexec_b64 s[24:25], s[40:41]
	s_cbranch_execz .LBB0_819
	v_lshl_add_u64 v[6:7], v[20:21], 2, s[46:47]
	s_waitcnt lgkmcnt(0)
	v_add_f32_e32 v4, v4, v5
	global_atomic_add_f32 v[6:7], v4, off

.LBB0_964:
	v_lshl_add_u32 v140, s87, 8, v3
	v_lshl_or_b32 v138, s86, 8, v147
	v_ashrrev_i32_e32 v141, 31, v140
	v_ashrrev_i32_e32 v139, 31, v138
	v_lshlrev_b64 v[142:143], 10, v[140:141]
	v_lshl_add_u64 v[144:145], v[142:143], 0, v[138:139]
	v_lshl_add_u64 v[142:143], v[144:145], 2, s[44:45]
	global_load_dwordx4 v[150:153], v[142:143], off nt
	global_load_dwordx4 v[154:157], v[142:143], off offset:16 nt
	s_mov_b64 s[24:25], -1
	s_and_b64 vcc, exec, s[0:1]
	s_waitcnt vmcnt(0)
	v_pk_add_f32 v[130:131], v[130:131], v[152:153]
	v_pk_add_f32 v[128:129], v[128:129], v[150:151]
	v_pk_add_f32 v[126:127], v[126:127], v[156:157]
	v_pk_add_f32 v[124:125], v[124:125], v[154:155]
	global_store_dwordx4 v[142:143], v[128:131], off
	global_store_dwordx4 v[142:143], v[124:127], off offset:16
	s_cbranch_vccz .LBB0_966
	global_load_dwordx4 v[150:153], v[142:143], off offset:512 nt
	global_load_dwordx4 v[154:157], v[142:143], off offset:528 nt
	s_mov_b64 s[24:25], 0
	s_waitcnt vmcnt(1)
	v_pk_add_f32 v[152:153], v[122:123], v[152:153]
	v_pk_add_f32 v[150:151], v[120:121], v[150:151]
	s_waitcnt vmcnt(0)
	v_pk_add_f32 v[156:157], v[118:119], v[156:157]
	v_pk_add_f32 v[154:155], v[116:117], v[154:155]
	global_store_dwordx4 v[142:143], v[150:153], off offset:512
	global_store_dwordx4 v[142:143], v[154:157], off offset:528
.LBB0_966:
	s_andn2_b64 vcc, exec, s[24:25]
	v_xor_b32_e32 v150, 16, v204
	v_and_b32_e32 v151, 64, v204
	v_xor_b32_e32 v149, 32, v204
	s_cbranch_vccnz .LBB0_970
	v_mul_f32_e32 v152, v129, v129
	v_mul_f32_e32 v153, v131, v131
	v_fmac_f32_e32 v152, v128, v128
	v_fmac_f32_e32 v153, v130, v130
	v_lshl_add_u64 v[144:145], v[144:145], 1, s[48:49]
	v_add_f32_e32 v152, v152, v153
	v_mul_f32_e32 v153, v125, v125
	v_mul_f32_e32 v154, v127, v127
	v_cvt_pk_bf16_f32 v128, v128, v129
	v_cvt_pk_bf16_f32 v129, v130, v131
	v_cvt_pk_bf16_f32 v130, v124, v125
	v_cvt_pk_bf16_f32 v131, v126, v127
	global_store_dwordx4 v[144:145], v[128:131], off
	v_fmac_f32_e32 v153, v124, v124
	v_fmac_f32_e32 v154, v126, v126
	global_load_dwordx4 v[124:127], v[142:143], off offset:528 nt
	global_load_dwordx4 v[128:131], v[142:143], off offset:512 nt
	v_add_f32_e32 v153, v153, v154
	v_add_f32_e32 v152, v152, v153
	s_waitcnt vmcnt(1)
	v_pk_add_f32 v[116:117], v[116:117], v[124:125]
	s_waitcnt vmcnt(0)
	v_pk_add_f32 v[122:123], v[122:123], v[130:131]
	v_pk_add_f32 v[120:121], v[120:121], v[128:129]
	v_mul_f32_e32 v125, v123, v123
	v_mul_f32_e32 v124, v121, v121
	v_pk_add_f32 v[118:119], v[118:119], v[126:127]
	v_fmac_f32_e32 v124, v120, v120
	v_fmac_f32_e32 v125, v122, v122
	v_add_f32_e32 v124, v124, v125
	v_mul_f32_e32 v125, v117, v117
	v_mul_f32_e32 v126, v119, v119
	global_store_dwordx4 v[142:143], v[120:123], off offset:512
	global_store_dwordx4 v[142:143], v[116:119], off offset:528
	v_fmac_f32_e32 v125, v116, v116
	v_fmac_f32_e32 v126, v118, v118
	v_cvt_pk_bf16_f32 v120, v120, v121
	v_cvt_pk_bf16_f32 v121, v122, v123
	v_cvt_pk_bf16_f32 v122, v116, v117
	v_add_u32_e32 v117, 64, v151
	v_add_f32_e32 v125, v125, v126
	v_cmp_lt_i32_e32 vcc, v150, v117
	v_add_f32_e32 v124, v124, v125
	v_add_f32_e32 v124, v152, v124
	v_cndmask_b32_e32 v116, v204, v150, vcc
	v_lshlrev_b32_e32 v116, 2, v116
	ds_bpermute_b32 v116, v116, v124
	v_cmp_lt_i32_e32 vcc, v149, v117
	v_cvt_pk_bf16_f32 v123, v118, v119
	global_store_dwordx4 v[144:145], v[120:123], off offset:256
	s_waitcnt lgkmcnt(0)
	v_add_f32_e32 v116, v124, v116
	v_cndmask_b32_e32 v117, v204, v149, vcc
	v_lshlrev_b32_e32 v117, 2, v117
	ds_bpermute_b32 v117, v117, v116
	s_and_saveexec_b64 s[24:25], s[38:39]
	s_cbranch_execz .LBB0_969
	v_lshl_add_u64 v[118:119], v[140:141], 2, s[46:47]
	s_waitcnt lgkmcnt(0)
	v_add_f32_e32 v116, v116, v117
	global_atomic_add_f32 v[118:119], v116, off

.LBB0_970:
	v_or_b32_e32 v116, 16, v140
	s_waitcnt lgkmcnt(0)
	v_ashrrev_i32_e32 v117, 31, v116
	v_lshlrev_b64 v[118:119], 10, v[116:117]
	v_lshl_add_u64 v[120:121], v[118:119], 0, v[138:139]
	v_lshl_add_u64 v[118:119], v[120:121], 2, s[44:45]
	global_load_dwordx4 v[122:125], v[118:119], off nt
	global_load_dwordx4 v[126:129], v[118:119], off offset:16 nt
	s_mov_b64 s[24:25], -1
	s_and_b64 vcc, exec, s[0:1]
	s_waitcnt vmcnt(1)
	v_pk_add_f32 v[114:115], v[114:115], v[124:125]
	v_pk_add_f32 v[112:113], v[112:113], v[122:123]
	s_waitcnt vmcnt(0)
	v_pk_add_f32 v[110:111], v[110:111], v[128:129]
	v_pk_add_f32 v[108:109], v[108:109], v[126:127]
	global_store_dwordx4 v[118:119], v[112:115], off
	global_store_dwordx4 v[118:119], v[108:111], off offset:16
	s_cbranch_vccz .LBB0_972
	global_load_dwordx4 v[122:125], v[118:119], off offset:512 nt
	global_load_dwordx4 v[126:129], v[118:119], off offset:528 nt
	s_mov_b64 s[24:25], 0
	s_waitcnt vmcnt(1)
	v_pk_add_f32 v[124:125], v[106:107], v[124:125]
	v_pk_add_f32 v[122:123], v[104:105], v[122:123]
	s_waitcnt vmcnt(0)
	v_pk_add_f32 v[128:129], v[102:103], v[128:129]
	v_pk_add_f32 v[126:127], v[100:101], v[126:127]
	global_store_dwordx4 v[118:119], v[122:125], off offset:512
	global_store_dwordx4 v[118:119], v[126:129], off offset:528
.LBB0_972:
	s_andn2_b64 vcc, exec, s[24:25]
	s_cbranch_vccnz .LBB0_976
	v_mul_f32_e32 v122, v113, v113
	v_mul_f32_e32 v123, v115, v115
	v_fmac_f32_e32 v122, v112, v112
	v_fmac_f32_e32 v123, v114, v114
	v_lshl_add_u64 v[120:121], v[120:121], 1, s[48:49]
	v_add_f32_e32 v122, v122, v123
	v_mul_f32_e32 v123, v109, v109
	v_mul_f32_e32 v124, v111, v111
	v_cvt_pk_bf16_f32 v112, v112, v113
	v_cvt_pk_bf16_f32 v113, v114, v115
	v_cvt_pk_bf16_f32 v114, v108, v109
	v_cvt_pk_bf16_f32 v115, v110, v111
	global_store_dwordx4 v[120:121], v[112:115], off
	v_fmac_f32_e32 v123, v108, v108
	v_fmac_f32_e32 v124, v110, v110
	global_load_dwordx4 v[108:111], v[118:119], off offset:528 nt
	global_load_dwordx4 v[112:115], v[118:119], off offset:512 nt
	v_add_f32_e32 v123, v123, v124
	v_add_f32_e32 v122, v122, v123
	s_waitcnt vmcnt(1)
	v_pk_add_f32 v[100:101], v[100:101], v[108:109]
	s_waitcnt vmcnt(0)
	v_pk_add_f32 v[106:107], v[106:107], v[114:115]
	v_pk_add_f32 v[104:105], v[104:105], v[112:113]
	v_mul_f32_e32 v109, v107, v107
	v_mul_f32_e32 v108, v105, v105
	v_pk_add_f32 v[102:103], v[102:103], v[110:111]
	v_fmac_f32_e32 v108, v104, v104
	v_fmac_f32_e32 v109, v106, v106
	v_add_f32_e32 v108, v108, v109
	v_mul_f32_e32 v109, v101, v101
	v_mul_f32_e32 v110, v103, v103
	global_store_dwordx4 v[118:119], v[104:107], off offset:512
	global_store_dwordx4 v[118:119], v[100:103], off offset:528
	v_fmac_f32_e32 v109, v100, v100
	v_fmac_f32_e32 v110, v102, v102
	v_cvt_pk_bf16_f32 v104, v104, v105
	v_cvt_pk_bf16_f32 v105, v106, v107
	v_cvt_pk_bf16_f32 v106, v100, v101
	v_add_u32_e32 v101, 64, v151
	v_add_f32_e32 v109, v109, v110
	v_cmp_lt_i32_e32 vcc, v150, v101
	v_add_f32_e32 v108, v108, v109
	v_add_f32_e32 v108, v122, v108
	v_cndmask_b32_e32 v100, v204, v150, vcc
	v_lshlrev_b32_e32 v100, 2, v100
	ds_bpermute_b32 v100, v100, v108
	v_cmp_lt_i32_e32 vcc, v149, v101
	v_cvt_pk_bf16_f32 v107, v102, v103
	global_store_dwordx4 v[120:121], v[104:107], off offset:256
	s_waitcnt lgkmcnt(0)
	v_add_f32_e32 v100, v108, v100
	v_cndmask_b32_e32 v101, v204, v149, vcc
	v_lshlrev_b32_e32 v101, 2, v101
	ds_bpermute_b32 v101, v101, v100
	s_and_saveexec_b64 s[24:25], s[38:39]
	s_cbranch_execz .LBB0_975
	v_lshl_add_u64 v[102:103], v[116:117], 2, s[46:47]
	s_waitcnt lgkmcnt(0)
	v_add_f32_e32 v100, v100, v101
	global_atomic_add_f32 v[102:103], v100, off

.LBB0_976:
	v_or_b32_e32 v100, 32, v140
	s_waitcnt lgkmcnt(0)
	v_ashrrev_i32_e32 v101, 31, v100
	v_lshlrev_b64 v[102:103], 10, v[100:101]
	v_lshl_add_u64 v[104:105], v[102:103], 0, v[138:139]
	v_lshl_add_u64 v[102:103], v[104:105], 2, s[44:45]
	global_load_dwordx4 v[106:109], v[102:103], off nt
	global_load_dwordx4 v[110:113], v[102:103], off offset:16 nt
	s_mov_b64 s[24:25], -1
	s_and_b64 vcc, exec, s[0:1]
	s_waitcnt vmcnt(1)
	v_pk_add_f32 v[98:99], v[98:99], v[108:109]
	v_pk_add_f32 v[96:97], v[96:97], v[106:107]
	s_waitcnt vmcnt(0)
	v_pk_add_f32 v[94:95], v[94:95], v[112:113]
	v_pk_add_f32 v[92:93], v[92:93], v[110:111]
	global_store_dwordx4 v[102:103], v[96:99], off
	global_store_dwordx4 v[102:103], v[92:95], off offset:16
	s_cbranch_vccz .LBB0_978
	global_load_dwordx4 v[106:109], v[102:103], off offset:512 nt
	global_load_dwordx4 v[110:113], v[102:103], off offset:528 nt
	s_mov_b64 s[24:25], 0
	s_waitcnt vmcnt(1)
	v_pk_add_f32 v[108:109], v[90:91], v[108:109]
	v_pk_add_f32 v[106:107], v[88:89], v[106:107]
	s_waitcnt vmcnt(0)
	v_pk_add_f32 v[112:113], v[86:87], v[112:113]
	v_pk_add_f32 v[110:111], v[84:85], v[110:111]
	global_store_dwordx4 v[102:103], v[106:109], off offset:512
	global_store_dwordx4 v[102:103], v[110:113], off offset:528
.LBB0_978:
	s_andn2_b64 vcc, exec, s[24:25]
	s_cbranch_vccnz .LBB0_982
	v_mul_f32_e32 v106, v97, v97
	v_mul_f32_e32 v107, v99, v99
	v_fmac_f32_e32 v106, v96, v96
	v_fmac_f32_e32 v107, v98, v98
	v_lshl_add_u64 v[104:105], v[104:105], 1, s[48:49]
	v_add_f32_e32 v106, v106, v107
	v_mul_f32_e32 v107, v93, v93
	v_mul_f32_e32 v108, v95, v95
	v_cvt_pk_bf16_f32 v96, v96, v97
	v_cvt_pk_bf16_f32 v97, v98, v99
	v_cvt_pk_bf16_f32 v98, v92, v93
	v_cvt_pk_bf16_f32 v99, v94, v95
	global_store_dwordx4 v[104:105], v[96:99], off
	v_fmac_f32_e32 v107, v92, v92
	v_fmac_f32_e32 v108, v94, v94
	global_load_dwordx4 v[92:95], v[102:103], off offset:528 nt
	global_load_dwordx4 v[96:99], v[102:103], off offset:512 nt
	v_add_f32_e32 v107, v107, v108
	v_add_f32_e32 v106, v106, v107
	s_waitcnt vmcnt(1)
	v_pk_add_f32 v[84:85], v[84:85], v[92:93]
	s_waitcnt vmcnt(0)
	v_pk_add_f32 v[90:91], v[90:91], v[98:99]
	v_pk_add_f32 v[88:89], v[88:89], v[96:97]
	v_mul_f32_e32 v93, v91, v91
	v_mul_f32_e32 v92, v89, v89
	v_pk_add_f32 v[86:87], v[86:87], v[94:95]
	v_fmac_f32_e32 v92, v88, v88
	v_fmac_f32_e32 v93, v90, v90
	v_add_f32_e32 v92, v92, v93
	v_mul_f32_e32 v93, v85, v85
	v_mul_f32_e32 v94, v87, v87
	global_store_dwordx4 v[102:103], v[88:91], off offset:512
	global_store_dwordx4 v[102:103], v[84:87], off offset:528
	v_fmac_f32_e32 v93, v84, v84
	v_fmac_f32_e32 v94, v86, v86
	v_cvt_pk_bf16_f32 v88, v88, v89
	v_cvt_pk_bf16_f32 v89, v90, v91
	v_cvt_pk_bf16_f32 v90, v84, v85
	v_add_u32_e32 v85, 64, v151
	v_add_f32_e32 v93, v93, v94
	v_cmp_lt_i32_e32 vcc, v150, v85
	v_add_f32_e32 v92, v92, v93
	v_add_f32_e32 v92, v106, v92
	v_cndmask_b32_e32 v84, v204, v150, vcc
	v_lshlrev_b32_e32 v84, 2, v84
	ds_bpermute_b32 v84, v84, v92
	v_cmp_lt_i32_e32 vcc, v149, v85
	v_cvt_pk_bf16_f32 v91, v86, v87
	global_store_dwordx4 v[104:105], v[88:91], off offset:256
	s_waitcnt lgkmcnt(0)
	v_add_f32_e32 v84, v92, v84
	v_cndmask_b32_e32 v85, v204, v149, vcc
	v_lshlrev_b32_e32 v85, 2, v85
	ds_bpermute_b32 v85, v85, v84
	s_and_saveexec_b64 s[24:25], s[38:39]
	s_cbranch_execz .LBB0_981
	v_lshl_add_u64 v[86:87], v[100:101], 2, s[46:47]
	s_waitcnt lgkmcnt(0)
	v_add_f32_e32 v84, v84, v85
	global_atomic_add_f32 v[86:87], v84, off

.LBB0_982:
	v_or_b32_e32 v84, 48, v140
	s_waitcnt lgkmcnt(0)
	v_ashrrev_i32_e32 v85, 31, v84
	v_lshlrev_b64 v[86:87], 10, v[84:85]
	v_lshl_add_u64 v[88:89], v[86:87], 0, v[138:139]
	v_lshl_add_u64 v[86:87], v[88:89], 2, s[44:45]
	global_load_dwordx4 v[90:93], v[86:87], off nt
	global_load_dwordx4 v[94:97], v[86:87], off offset:16 nt
	s_mov_b64 s[24:25], -1
	s_and_b64 vcc, exec, s[0:1]
	s_waitcnt vmcnt(1)
	v_pk_add_f32 v[82:83], v[82:83], v[92:93]
	v_pk_add_f32 v[80:81], v[80:81], v[90:91]
	s_waitcnt vmcnt(0)
	v_pk_add_f32 v[78:79], v[78:79], v[96:97]
	v_pk_add_f32 v[76:77], v[76:77], v[94:95]
	global_store_dwordx4 v[86:87], v[80:83], off
	global_store_dwordx4 v[86:87], v[76:79], off offset:16
	s_cbranch_vccz .LBB0_984
	global_load_dwordx4 v[90:93], v[86:87], off offset:512 nt
	global_load_dwordx4 v[94:97], v[86:87], off offset:528 nt
	s_mov_b64 s[24:25], 0
	s_waitcnt vmcnt(1)
	v_pk_add_f32 v[92:93], v[74:75], v[92:93]
	v_pk_add_f32 v[90:91], v[72:73], v[90:91]
	s_waitcnt vmcnt(0)
	v_pk_add_f32 v[96:97], v[70:71], v[96:97]
	v_pk_add_f32 v[94:95], v[68:69], v[94:95]
	global_store_dwordx4 v[86:87], v[90:93], off offset:512
	global_store_dwordx4 v[86:87], v[94:97], off offset:528
.LBB0_984:
	s_andn2_b64 vcc, exec, s[24:25]
	s_cbranch_vccnz .LBB0_988
	v_mul_f32_e32 v90, v81, v81
	v_mul_f32_e32 v91, v83, v83
	v_fmac_f32_e32 v90, v80, v80
	v_fmac_f32_e32 v91, v82, v82
	v_lshl_add_u64 v[88:89], v[88:89], 1, s[48:49]
	v_add_f32_e32 v90, v90, v91
	v_mul_f32_e32 v91, v77, v77
	v_mul_f32_e32 v92, v79, v79
	v_cvt_pk_bf16_f32 v80, v80, v81
	v_cvt_pk_bf16_f32 v81, v82, v83
	v_cvt_pk_bf16_f32 v82, v76, v77
	v_cvt_pk_bf16_f32 v83, v78, v79
	global_store_dwordx4 v[88:89], v[80:83], off
	v_fmac_f32_e32 v91, v76, v76
	v_fmac_f32_e32 v92, v78, v78
	global_load_dwordx4 v[76:79], v[86:87], off offset:528 nt
	global_load_dwordx4 v[80:83], v[86:87], off offset:512 nt
	v_add_f32_e32 v91, v91, v92
	v_add_f32_e32 v90, v90, v91
	s_waitcnt vmcnt(1)
	v_pk_add_f32 v[68:69], v[68:69], v[76:77]
	s_waitcnt vmcnt(0)
	v_pk_add_f32 v[74:75], v[74:75], v[82:83]
	v_pk_add_f32 v[72:73], v[72:73], v[80:81]
	v_mul_f32_e32 v77, v75, v75
	v_mul_f32_e32 v76, v73, v73
	v_pk_add_f32 v[70:71], v[70:71], v[78:79]
	v_fmac_f32_e32 v76, v72, v72
	v_fmac_f32_e32 v77, v74, v74
	v_add_f32_e32 v76, v76, v77
	v_mul_f32_e32 v77, v69, v69
	v_mul_f32_e32 v78, v71, v71
	global_store_dwordx4 v[86:87], v[72:75], off offset:512
	global_store_dwordx4 v[86:87], v[68:71], off offset:528
	v_fmac_f32_e32 v77, v68, v68
	v_fmac_f32_e32 v78, v70, v70
	v_cvt_pk_bf16_f32 v72, v72, v73
	v_cvt_pk_bf16_f32 v73, v74, v75
	v_cvt_pk_bf16_f32 v74, v68, v69
	v_add_u32_e32 v69, 64, v151
	v_add_f32_e32 v77, v77, v78
	v_cmp_lt_i32_e32 vcc, v150, v69
	v_add_f32_e32 v76, v76, v77
	v_add_f32_e32 v76, v90, v76
	v_cndmask_b32_e32 v68, v204, v150, vcc
	v_lshlrev_b32_e32 v68, 2, v68
	ds_bpermute_b32 v68, v68, v76
	v_cmp_lt_i32_e32 vcc, v149, v69
	v_cvt_pk_bf16_f32 v75, v70, v71
	global_store_dwordx4 v[88:89], v[72:75], off offset:256
	s_waitcnt lgkmcnt(0)
	v_add_f32_e32 v68, v76, v68
	v_cndmask_b32_e32 v69, v204, v149, vcc
	v_lshlrev_b32_e32 v69, 2, v69
	ds_bpermute_b32 v69, v69, v68
	s_and_saveexec_b64 s[24:25], s[38:39]
	s_cbranch_execz .LBB0_987
	v_lshl_add_u64 v[70:71], v[84:85], 2, s[46:47]
	s_waitcnt lgkmcnt(0)
	v_add_f32_e32 v68, v68, v69
	global_atomic_add_f32 v[70:71], v68, off

.LBB0_988:
	v_add_u32_e32 v68, 0x80, v140
	s_waitcnt lgkmcnt(0)
	v_ashrrev_i32_e32 v69, 31, v68
	v_lshlrev_b64 v[70:71], 10, v[68:69]
	v_lshl_add_u64 v[72:73], v[70:71], 0, v[138:139]
	v_lshl_add_u64 v[70:71], v[72:73], 2, s[44:45]
	global_load_dwordx4 v[74:77], v[70:71], off nt
	global_load_dwordx4 v[78:81], v[70:71], off offset:16 nt
	s_mov_b64 s[24:25], -1
	s_and_b64 vcc, exec, s[0:1]
	s_waitcnt vmcnt(1)
	v_pk_add_f32 v[66:67], v[66:67], v[76:77]
	v_pk_add_f32 v[64:65], v[64:65], v[74:75]
	s_waitcnt vmcnt(0)
	v_pk_add_f32 v[62:63], v[62:63], v[80:81]
	v_pk_add_f32 v[60:61], v[60:61], v[78:79]
	global_store_dwordx4 v[70:71], v[64:67], off
	global_store_dwordx4 v[70:71], v[60:63], off offset:16
	s_cbranch_vccz .LBB0_990
	global_load_dwordx4 v[74:77], v[70:71], off offset:512 nt
	global_load_dwordx4 v[78:81], v[70:71], off offset:528 nt
	s_mov_b64 s[24:25], 0
	s_waitcnt vmcnt(1)
	v_pk_add_f32 v[76:77], v[58:59], v[76:77]
	v_pk_add_f32 v[74:75], v[56:57], v[74:75]
	s_waitcnt vmcnt(0)
	v_pk_add_f32 v[80:81], v[54:55], v[80:81]
	v_pk_add_f32 v[78:79], v[52:53], v[78:79]
	global_store_dwordx4 v[70:71], v[74:77], off offset:512
	global_store_dwordx4 v[70:71], v[78:81], off offset:528
.LBB0_990:
	s_andn2_b64 vcc, exec, s[24:25]
	s_cbranch_vccnz .LBB0_994
	v_mul_f32_e32 v74, v65, v65
	v_mul_f32_e32 v75, v67, v67
	v_fmac_f32_e32 v74, v64, v64
	v_fmac_f32_e32 v75, v66, v66
	v_lshl_add_u64 v[72:73], v[72:73], 1, s[48:49]
	v_add_f32_e32 v74, v74, v75
	v_mul_f32_e32 v75, v61, v61
	v_mul_f32_e32 v76, v63, v63
	v_cvt_pk_bf16_f32 v64, v64, v65
	v_cvt_pk_bf16_f32 v65, v66, v67
	v_cvt_pk_bf16_f32 v66, v60, v61
	v_cvt_pk_bf16_f32 v67, v62, v63
	global_store_dwordx4 v[72:73], v[64:67], off
	v_fmac_f32_e32 v75, v60, v60
	v_fmac_f32_e32 v76, v62, v62
	global_load_dwordx4 v[60:63], v[70:71], off offset:528 nt
	global_load_dwordx4 v[64:67], v[70:71], off offset:512 nt
	v_add_f32_e32 v75, v75, v76
	v_add_f32_e32 v74, v74, v75
	s_waitcnt vmcnt(1)
	v_pk_add_f32 v[52:53], v[52:53], v[60:61]
	s_waitcnt vmcnt(0)
	v_pk_add_f32 v[58:59], v[58:59], v[66:67]
	v_pk_add_f32 v[56:57], v[56:57], v[64:65]
	v_mul_f32_e32 v61, v59, v59
	v_mul_f32_e32 v60, v57, v57
	v_pk_add_f32 v[54:55], v[54:55], v[62:63]
	v_fmac_f32_e32 v60, v56, v56
	v_fmac_f32_e32 v61, v58, v58
	v_add_f32_e32 v60, v60, v61
	v_mul_f32_e32 v61, v53, v53
	v_mul_f32_e32 v62, v55, v55
	global_store_dwordx4 v[70:71], v[56:59], off offset:512
	global_store_dwordx4 v[70:71], v[52:55], off offset:528
	v_fmac_f32_e32 v61, v52, v52
	v_fmac_f32_e32 v62, v54, v54
	v_cvt_pk_bf16_f32 v56, v56, v57
	v_cvt_pk_bf16_f32 v57, v58, v59
	v_cvt_pk_bf16_f32 v58, v52, v53
	v_add_u32_e32 v53, 64, v151
	v_add_f32_e32 v61, v61, v62
	v_cmp_lt_i32_e32 vcc, v150, v53
	v_add_f32_e32 v60, v60, v61
	v_add_f32_e32 v60, v74, v60
	v_cndmask_b32_e32 v52, v204, v150, vcc
	v_lshlrev_b32_e32 v52, 2, v52
	ds_bpermute_b32 v52, v52, v60
	v_cmp_lt_i32_e32 vcc, v149, v53
	v_cvt_pk_bf16_f32 v59, v54, v55
	global_store_dwordx4 v[72:73], v[56:59], off offset:256
	s_waitcnt lgkmcnt(0)
	v_add_f32_e32 v52, v60, v52
	v_cndmask_b32_e32 v53, v204, v149, vcc
	v_lshlrev_b32_e32 v53, 2, v53
	ds_bpermute_b32 v53, v53, v52
	s_and_saveexec_b64 s[24:25], s[38:39]
	s_cbranch_execz .LBB0_993
	v_lshl_add_u64 v[54:55], v[68:69], 2, s[46:47]
	s_waitcnt lgkmcnt(0)
	v_add_f32_e32 v52, v52, v53
	global_atomic_add_f32 v[54:55], v52, off

.LBB0_994:
	v_add_u32_e32 v52, 0x90, v140
	s_waitcnt lgkmcnt(0)
	v_ashrrev_i32_e32 v53, 31, v52
	v_lshlrev_b64 v[54:55], 10, v[52:53]
	v_lshl_add_u64 v[56:57], v[54:55], 0, v[138:139]
	v_lshl_add_u64 v[54:55], v[56:57], 2, s[44:45]
	global_load_dwordx4 v[58:61], v[54:55], off nt
	global_load_dwordx4 v[62:65], v[54:55], off offset:16 nt
	s_mov_b64 s[24:25], -1
	s_and_b64 vcc, exec, s[0:1]
	s_waitcnt vmcnt(1)
	v_pk_add_f32 v[50:51], v[50:51], v[60:61]
	v_pk_add_f32 v[48:49], v[48:49], v[58:59]
	s_waitcnt vmcnt(0)
	v_pk_add_f32 v[46:47], v[46:47], v[64:65]
	v_pk_add_f32 v[44:45], v[44:45], v[62:63]
	global_store_dwordx4 v[54:55], v[48:51], off
	global_store_dwordx4 v[54:55], v[44:47], off offset:16
	s_cbranch_vccz .LBB0_996
	global_load_dwordx4 v[58:61], v[54:55], off offset:512 nt
	global_load_dwordx4 v[62:65], v[54:55], off offset:528 nt
	s_mov_b64 s[24:25], 0
	s_waitcnt vmcnt(1)
	v_pk_add_f32 v[60:61], v[42:43], v[60:61]
	v_pk_add_f32 v[58:59], v[40:41], v[58:59]
	s_waitcnt vmcnt(0)
	v_pk_add_f32 v[64:65], v[38:39], v[64:65]
	v_pk_add_f32 v[62:63], v[36:37], v[62:63]
	global_store_dwordx4 v[54:55], v[58:61], off offset:512
	global_store_dwordx4 v[54:55], v[62:65], off offset:528
.LBB0_996:
	s_andn2_b64 vcc, exec, s[24:25]
	s_cbranch_vccnz .LBB0_1000
	v_mul_f32_e32 v58, v49, v49
	v_mul_f32_e32 v59, v51, v51
	v_fmac_f32_e32 v58, v48, v48
	v_fmac_f32_e32 v59, v50, v50
	v_lshl_add_u64 v[56:57], v[56:57], 1, s[48:49]
	v_add_f32_e32 v58, v58, v59
	v_mul_f32_e32 v59, v45, v45
	v_mul_f32_e32 v60, v47, v47
	v_cvt_pk_bf16_f32 v48, v48, v49
	v_cvt_pk_bf16_f32 v49, v50, v51
	v_cvt_pk_bf16_f32 v50, v44, v45
	v_cvt_pk_bf16_f32 v51, v46, v47
	global_store_dwordx4 v[56:57], v[48:51], off
	v_fmac_f32_e32 v59, v44, v44
	v_fmac_f32_e32 v60, v46, v46
	global_load_dwordx4 v[44:47], v[54:55], off offset:528 nt
	global_load_dwordx4 v[48:51], v[54:55], off offset:512 nt
	v_add_f32_e32 v59, v59, v60
	v_add_f32_e32 v58, v58, v59
	s_waitcnt vmcnt(1)
	v_pk_add_f32 v[36:37], v[36:37], v[44:45]
	s_waitcnt vmcnt(0)
	v_pk_add_f32 v[42:43], v[42:43], v[50:51]
	v_pk_add_f32 v[40:41], v[40:41], v[48:49]
	v_mul_f32_e32 v45, v43, v43
	v_mul_f32_e32 v44, v41, v41
	v_pk_add_f32 v[38:39], v[38:39], v[46:47]
	v_fmac_f32_e32 v44, v40, v40
	v_fmac_f32_e32 v45, v42, v42
	v_add_f32_e32 v44, v44, v45
	v_mul_f32_e32 v45, v37, v37
	v_mul_f32_e32 v46, v39, v39
	global_store_dwordx4 v[54:55], v[40:43], off offset:512
	global_store_dwordx4 v[54:55], v[36:39], off offset:528
	v_fmac_f32_e32 v45, v36, v36
	v_fmac_f32_e32 v46, v38, v38
	v_cvt_pk_bf16_f32 v40, v40, v41
	v_cvt_pk_bf16_f32 v41, v42, v43
	v_cvt_pk_bf16_f32 v42, v36, v37
	v_add_u32_e32 v37, 64, v151
	v_add_f32_e32 v45, v45, v46
	v_cmp_lt_i32_e32 vcc, v150, v37
	v_add_f32_e32 v44, v44, v45
	v_add_f32_e32 v44, v58, v44
	v_cndmask_b32_e32 v36, v204, v150, vcc
	v_lshlrev_b32_e32 v36, 2, v36
	ds_bpermute_b32 v36, v36, v44
	v_cmp_lt_i32_e32 vcc, v149, v37
	v_cvt_pk_bf16_f32 v43, v38, v39
	global_store_dwordx4 v[56:57], v[40:43], off offset:256
	s_waitcnt lgkmcnt(0)
	v_add_f32_e32 v36, v44, v36
	v_cndmask_b32_e32 v37, v204, v149, vcc
	v_lshlrev_b32_e32 v37, 2, v37
	ds_bpermute_b32 v37, v37, v36
	s_and_saveexec_b64 s[24:25], s[38:39]
	s_cbranch_execz .LBB0_999
	v_lshl_add_u64 v[38:39], v[52:53], 2, s[46:47]
	s_waitcnt lgkmcnt(0)
	v_add_f32_e32 v36, v36, v37
	global_atomic_add_f32 v[38:39], v36, off

.LBB0_1000:
	v_add_u32_e32 v36, 0xa0, v140
	s_waitcnt lgkmcnt(0)
	v_ashrrev_i32_e32 v37, 31, v36
	v_lshlrev_b64 v[38:39], 10, v[36:37]
	v_lshl_add_u64 v[40:41], v[38:39], 0, v[138:139]
	v_lshl_add_u64 v[38:39], v[40:41], 2, s[44:45]
	global_load_dwordx4 v[42:45], v[38:39], off nt
	global_load_dwordx4 v[46:49], v[38:39], off offset:16 nt
	s_mov_b64 s[24:25], -1
	s_and_b64 vcc, exec, s[0:1]
	s_waitcnt vmcnt(1)
	v_pk_add_f32 v[34:35], v[34:35], v[44:45]
	v_pk_add_f32 v[32:33], v[32:33], v[42:43]
	s_waitcnt vmcnt(0)
	v_pk_add_f32 v[30:31], v[30:31], v[48:49]
	v_pk_add_f32 v[28:29], v[28:29], v[46:47]
	global_store_dwordx4 v[38:39], v[32:35], off
	global_store_dwordx4 v[38:39], v[28:31], off offset:16
	s_cbranch_vccz .LBB0_1002
	global_load_dwordx4 v[42:45], v[38:39], off offset:512 nt
	global_load_dwordx4 v[46:49], v[38:39], off offset:528 nt
	s_mov_b64 s[24:25], 0
	s_waitcnt vmcnt(1)
	v_pk_add_f32 v[44:45], v[26:27], v[44:45]
	v_pk_add_f32 v[42:43], v[24:25], v[42:43]
	s_waitcnt vmcnt(0)
	v_pk_add_f32 v[48:49], v[22:23], v[48:49]
	v_pk_add_f32 v[46:47], v[20:21], v[46:47]
	global_store_dwordx4 v[38:39], v[42:45], off offset:512
	global_store_dwordx4 v[38:39], v[46:49], off offset:528
.LBB0_1002:
	s_andn2_b64 vcc, exec, s[24:25]
	s_cbranch_vccnz .LBB0_1006
	v_mul_f32_e32 v42, v33, v33
	v_mul_f32_e32 v43, v35, v35
	v_fmac_f32_e32 v42, v32, v32
	v_fmac_f32_e32 v43, v34, v34
	v_lshl_add_u64 v[40:41], v[40:41], 1, s[48:49]
	v_add_f32_e32 v42, v42, v43
	v_mul_f32_e32 v43, v29, v29
	v_mul_f32_e32 v44, v31, v31
	v_cvt_pk_bf16_f32 v32, v32, v33
	v_cvt_pk_bf16_f32 v33, v34, v35
	v_cvt_pk_bf16_f32 v34, v28, v29
	v_cvt_pk_bf16_f32 v35, v30, v31
	global_store_dwordx4 v[40:41], v[32:35], off
	v_fmac_f32_e32 v43, v28, v28
	v_fmac_f32_e32 v44, v30, v30
	global_load_dwordx4 v[28:31], v[38:39], off offset:528 nt
	global_load_dwordx4 v[32:35], v[38:39], off offset:512 nt
	v_add_f32_e32 v43, v43, v44
	v_add_f32_e32 v42, v42, v43
	s_waitcnt vmcnt(1)
	v_pk_add_f32 v[20:21], v[20:21], v[28:29]
	s_waitcnt vmcnt(0)
	v_pk_add_f32 v[26:27], v[26:27], v[34:35]
	v_pk_add_f32 v[24:25], v[24:25], v[32:33]
	v_mul_f32_e32 v29, v27, v27
	v_mul_f32_e32 v28, v25, v25
	v_pk_add_f32 v[22:23], v[22:23], v[30:31]
	v_fmac_f32_e32 v28, v24, v24
	v_fmac_f32_e32 v29, v26, v26
	v_add_f32_e32 v28, v28, v29
	v_mul_f32_e32 v29, v21, v21
	v_mul_f32_e32 v30, v23, v23
	global_store_dwordx4 v[38:39], v[24:27], off offset:512
	global_store_dwordx4 v[38:39], v[20:23], off offset:528
	v_fmac_f32_e32 v29, v20, v20
	v_fmac_f32_e32 v30, v22, v22
	v_cvt_pk_bf16_f32 v24, v24, v25
	v_cvt_pk_bf16_f32 v25, v26, v27
	v_cvt_pk_bf16_f32 v26, v20, v21
	v_add_u32_e32 v21, 64, v151
	v_add_f32_e32 v29, v29, v30
	v_cmp_lt_i32_e32 vcc, v150, v21
	v_add_f32_e32 v28, v28, v29
	v_add_f32_e32 v28, v42, v28
	v_cndmask_b32_e32 v20, v204, v150, vcc
	v_lshlrev_b32_e32 v20, 2, v20
	ds_bpermute_b32 v20, v20, v28
	v_cmp_lt_i32_e32 vcc, v149, v21
	v_cvt_pk_bf16_f32 v27, v22, v23
	global_store_dwordx4 v[40:41], v[24:27], off offset:256
	s_waitcnt lgkmcnt(0)
	v_add_f32_e32 v20, v28, v20
	v_cndmask_b32_e32 v21, v204, v149, vcc
	v_lshlrev_b32_e32 v21, 2, v21
	ds_bpermute_b32 v21, v21, v20
	s_and_saveexec_b64 s[24:25], s[38:39]
	s_cbranch_execz .LBB0_1005
	v_lshl_add_u64 v[22:23], v[36:37], 2, s[46:47]
	s_waitcnt lgkmcnt(0)
	v_add_f32_e32 v20, v20, v21
	global_atomic_add_f32 v[22:23], v20, off

.LBB0_1006:
	v_add_u32_e32 v20, 0xb0, v140
	s_waitcnt lgkmcnt(0)
	v_ashrrev_i32_e32 v21, 31, v20
	v_lshlrev_b64 v[22:23], 10, v[20:21]
	v_lshl_add_u64 v[24:25], v[22:23], 0, v[138:139]
	v_lshl_add_u64 v[22:23], v[24:25], 2, s[44:45]
	global_load_dwordx4 v[26:29], v[22:23], off nt
	global_load_dwordx4 v[30:33], v[22:23], off offset:16 nt
	s_mov_b64 s[24:25], -1
	s_and_b64 vcc, exec, s[0:1]
	s_waitcnt vmcnt(1)
	v_pk_add_f32 v[18:19], v[18:19], v[28:29]
	v_pk_add_f32 v[16:17], v[16:17], v[26:27]
	s_waitcnt vmcnt(0)
	v_pk_add_f32 v[14:15], v[14:15], v[32:33]
	v_pk_add_f32 v[12:13], v[12:13], v[30:31]
	global_store_dwordx4 v[22:23], v[16:19], off
	global_store_dwordx4 v[22:23], v[12:15], off offset:16
	s_cbranch_vccnz .LBB0_1009
	s_andn2_b64 vcc, exec, s[24:25]
	s_cbranch_vccz .LBB0_1010

.LBB0_1009:
	global_load_dwordx4 v[26:29], v[22:23], off offset:512 nt
	global_load_dwordx4 v[30:33], v[22:23], off offset:528 nt
	s_waitcnt vmcnt(1)
	v_pk_add_f32 v[28:29], v[10:11], v[28:29]
	v_pk_add_f32 v[26:27], v[8:9], v[26:27]
	s_waitcnt vmcnt(0)
	v_pk_add_f32 v[32:33], v[6:7], v[32:33]
	v_pk_add_f32 v[30:31], v[4:5], v[30:31]
	global_store_dwordx4 v[22:23], v[26:29], off offset:512
	global_store_dwordx4 v[22:23], v[30:33], off offset:528
	s_cbranch_execnz .LBB0_1008
.LBB0_1010:
	v_mul_f32_e32 v26, v17, v17
	v_mul_f32_e32 v27, v19, v19
	v_fmac_f32_e32 v26, v16, v16
	v_fmac_f32_e32 v27, v18, v18
	v_lshl_add_u64 v[24:25], v[24:25], 1, s[48:49]
	v_add_f32_e32 v26, v26, v27
	v_mul_f32_e32 v27, v13, v13
	v_mul_f32_e32 v28, v15, v15
	v_cvt_pk_bf16_f32 v16, v16, v17
	v_cvt_pk_bf16_f32 v17, v18, v19
	v_cvt_pk_bf16_f32 v18, v12, v13
	v_cvt_pk_bf16_f32 v19, v14, v15
	global_store_dwordx4 v[24:25], v[16:19], off
	v_fmac_f32_e32 v27, v12, v12
	v_fmac_f32_e32 v28, v14, v14
	global_load_dwordx4 v[12:15], v[22:23], off offset:528 nt
	global_load_dwordx4 v[16:19], v[22:23], off offset:512 nt
	v_add_f32_e32 v27, v27, v28
	v_add_f32_e32 v26, v26, v27
	s_waitcnt vmcnt(1)
	v_pk_add_f32 v[4:5], v[4:5], v[12:13]
	s_waitcnt vmcnt(0)
	v_pk_add_f32 v[10:11], v[10:11], v[18:19]
	v_pk_add_f32 v[8:9], v[8:9], v[16:17]
	v_mul_f32_e32 v13, v11, v11
	v_mul_f32_e32 v12, v9, v9
	v_pk_add_f32 v[6:7], v[6:7], v[14:15]
	v_fmac_f32_e32 v12, v8, v8
	v_fmac_f32_e32 v13, v10, v10
	v_add_f32_e32 v12, v12, v13
	v_mul_f32_e32 v13, v5, v5
	v_mul_f32_e32 v14, v7, v7
	global_store_dwordx4 v[22:23], v[8:11], off offset:512
	global_store_dwordx4 v[22:23], v[4:7], off offset:528
	v_fmac_f32_e32 v13, v4, v4
	v_fmac_f32_e32 v14, v6, v6
	v_cvt_pk_bf16_f32 v8, v8, v9
	v_cvt_pk_bf16_f32 v9, v10, v11
	v_cvt_pk_bf16_f32 v10, v4, v5
	v_add_u32_e32 v5, 64, v151
	v_add_f32_e32 v13, v13, v14
	v_cmp_lt_i32_e32 vcc, v150, v5
	v_add_f32_e32 v12, v12, v13
	v_add_f32_e32 v12, v26, v12
	v_cndmask_b32_e32 v4, v204, v150, vcc
	v_lshlrev_b32_e32 v4, 2, v4
	ds_bpermute_b32 v4, v4, v12
	v_cmp_lt_i32_e32 vcc, v149, v5
	v_cvt_pk_bf16_f32 v11, v6, v7
	global_store_dwordx4 v[24:25], v[8:11], off offset:256
	s_waitcnt lgkmcnt(0)
	v_add_f32_e32 v4, v12, v4
	v_cndmask_b32_e32 v5, v204, v149, vcc
	v_lshlrev_b32_e32 v5, 2, v5
	ds_bpermute_b32 v5, v5, v4
	s_and_saveexec_b64 s[24:25], s[38:39]
	s_cbranch_execz .LBB0_1012
	v_lshl_add_u64 v[6:7], v[20:21], 2, s[46:47]
	s_waitcnt lgkmcnt(0)
	v_add_f32_e32 v4, v4, v5
	global_atomic_add_f32 v[6:7], v4, off
